# scan1: final 64x64 state staged through LDS so each global store writes four whole rows
# baseline (speedup 1.0000x reference)
; #define LAS __attribute__((address_space(3)))
; template <int NV, bool WITH_Y, int CH>
; __device__ __forceinline__ void scan_run(f32x2 (&S)[4][8], const unsigned char* oh  , LAS float* wl, float* yout  , int lane) {
;     const int Lc = lane < 56 ? lane : 55, cch = Lc - 16;
;     const bool isw = lane < 16, act = lane < 56;
;     const unsigned char* g0 = oh + Lc * 16;
;     LAS float* l0 = wl + (isw ? 64 + lane * 4 : ((cch >> 3) == 0 ? 0 : 64 + (cch >> 3) * 64) + (cch & 7) * 8);
;     const int cs16 = (lane & 3) * 16, rg4 = (lane >> 2) * 4;
;     u32x4 pa[CH];
; #pragma unroll
;     for (int st = 0; st < CH; ++st) pa[st] = *(const u32x4*)(g0 + (size_t)st * OPTB);
; __device__ __forceinline__ void phase_scan1(const Params& p, const Lt& lt, unsigned char* lds) {
;     ...
;     for (int j = w; j < nslot; j += 8) {
;         int lane = tid & 63; asm volatile("" : "+v"(lane));
;         const int kind = (j ^ (j >> 3)) & 1;
;         const int rank = j >> 1;
;         const int pair = rank * G + lt.bid;
;         if (pair >= NH * NSEG) continue;
;         const int h = pair / NSEG, g = pair % NSEG, row0 = (lane >> 2) * 4, col0 = (lane & 3) * 16;
;         f32x2 S[4][8];
;         const unsigned char* oh = opnd + (size_t)g * SEGLEN * OPTB + h * OPB;
;         float* dst = (kind == 0 ? TG : LG) + (size_t)(h * NSEG + g) * 4096 + row0 * 64 + col0;
;         if (kind == 0) {
; #pragma unroll
;             for (int r = 0; r < 4; ++r)
; #pragma unroll
;                 for (int q = 0; q < 8; ++q) S[r][q] = (f32x2){(row0 + r == col0 + 2 * q) ? 1.f : 0.f, (row0 + r == col0 + 2 * q + 1) ? 1.f : 0.f};
;             scan_run<3, true, 4>(S, oh, wl, (float*)(p.ws + WS_Z) + (size_t)g * SEGLEN * RW + h * 64, lane);
;         } else {
; #pragma unroll
;             for (int r = 0; r < 4; ++r)
; #pragma unroll
;                 for (int q = 0; q < 8; ++q) S[r][q] = (f32x2){0.f, 0.f};
.LBB0_265:
	s_ashr_i32 s0, s38, 1
	s_mul_i32 s0, s0, s89
	s_add_i32 s0, s0, s86
	s_cmpk_gt_i32 s0, 0x5ff
	s_cbranch_scc1 .LBB0_264
	s_ashr_i32 s4, s0, 31
	s_lshr_b32 s4, s4, 25
	s_add_i32 s4, s0, s4
	s_lshr_b32 s1, s38, 3
	s_ashr_i32 s47, s4, 7
	s_and_b32 s4, s4, 0xffffff80
	s_xor_b32 s1, s1, s38
	s_sub_i32 s48, s0, s4
	s_and_b32 s1, s1, 1
	s_mul_i32 s4, s48, 0xa8000
	s_mul_hi_i32 s0, s48, 0xa8000
	s_add_u32 s4, s40, s4
	s_mul_i32 s5, s47, 0x380
	s_addc_u32 s0, s41, s0
	s_ashr_i32 s6, s5, 31
	s_add_u32 s30, s4, s5
	s_addc_u32 s31, s0, s6
	s_mul_hi_i32 s49, s48, 0x30000
	s_mul_i32 s50, s48, 0x30000
	s_cmp_eq_u32 s1, 0
	s_cselect_b64 s[28:29], -1, 0
	s_cselect_b32 s34, s45, s42
	s_cselect_b32 s35, s46, s43
	s_cselect_b32 s36, 0, 1.0
	s_cselect_b32 s37, 1.0, 0
	s_lshl_b32 s0, s47, 8
	s_add_u32 s34, s34, s0
	s_addc_u32 s35, s35, 0
	s_add_u32 s34, s34, s50
	s_addc_u32 s35, s35, s49
	v_mov_b32_e32 v0, v106
	v_mov_b32_e32 v1, 0
	v_lshl_add_u64 v[10:11], v[0:1], 2, s[34:35]
	v_min_i32_e32 v2, 55, v106
	v_lshlrev_b32_e32 v0, 4, v2
	v_lshl_add_u64 v[4:5], s[30:31], 0, v[0:1]
	v_add_u32_e32 v0, -16, v2
	v_lshlrev_b32_e32 v1, 3, v0
	v_and_b32_e32 v1, 0xffffffc0, v1
	v_add_u32_e32 v1, 64, v1
	v_cmp_lt_u32_e32 vcc, 7, v0
	s_nop 1
	v_cndmask_b32_e32 v1, 0, v1, vcc
	v_lshlrev_b32_e32 v0, 3, v2
	v_and_or_b32 v1, v0, 56, v1
	v_lshl_add_u32 v0, v106, 2, 64
	v_cmp_gt_u32_e32 vcc, 16, v106
	s_nop 1
	v_cndmask_b32_e32 v1, v1, v0, vcc
	v_lshl_add_u32 v6, v1, 2, s39
	v_and_b32_e32 v206, 31, v106
	v_lshrrev_b32_e32 v207, 5, v106
	v_lshl_add_u32 v7, v207, 4, s39
	v_lshlrev_b32_e32 v0, 8, v207
	v_lshl_add_u32 v0, v206, 2, v0
	v_add_u32_e32 v8, s39, v0
	v_lshl_add_u32 v9, v106, 2, s39
	v_lshlrev_b32_e32 v0, 2, v207
	v_sub_u32_e32 v204, v206, v0
	v_mov_b32_e32 v199, s37
	s_mov_b32 s51, 0
	s_mov_b32 s10, 0
	v_lshl_add_u64 v[32:33], v[4:5], 0, s[10:11]
	v_add_co_u32_e32 v34, vcc, s71, v32
	s_nop 1
	v_addc_co_u32_e32 v35, vcc, 0, v33, vcc
	global_load_dwordx4 v[12:15], v[32:33], off
	global_load_dwordx4 v[16:19], v[34:35], off offset:2560
	v_add_co_u32_e32 v34, vcc, 0x5000, v32
	s_nop 1
	v_addc_co_u32_e32 v35, vcc, 0, v33, vcc
	global_load_dwordx4 v[20:23], v[34:35], off offset:1024
	v_add_co_u32_e32 v34, vcc, 0x7000, v32
	s_nop 1
	v_addc_co_u32_e32 v35, vcc, 0, v33, vcc
	global_load_dwordx4 v[24:27], v[34:35], off offset:3584
	v_cmp_eq_u32_e32 vcc, 0, v204
	s_nop 1
	v_cndmask_b32_e32 v128, 0, v199, vcc
	v_cmp_eq_u32_e32 vcc, 1, v204
	s_nop 1
	v_cndmask_b32_e32 v129, 0, v199, vcc
	v_cmp_eq_u32_e32 vcc, 2, v204
	s_nop 1
	v_cndmask_b32_e32 v130, 0, v199, vcc
	v_cmp_eq_u32_e32 vcc, 3, v204
	s_nop 1
	v_cndmask_b32_e32 v131, 0, v199, vcc
	v_cmp_eq_u32_e32 vcc, 8, v204
	s_nop 1
	v_cndmask_b32_e32 v132, 0, v199, vcc
	v_cmp_eq_u32_e32 vcc, 9, v204
	s_nop 1
	v_cndmask_b32_e32 v133, 0, v199, vcc
	v_cmp_eq_u32_e32 vcc, 10, v204
	s_nop 1
	v_cndmask_b32_e32 v134, 0, v199, vcc
	v_cmp_eq_u32_e32 vcc, 11, v204
	s_nop 1
	v_cndmask_b32_e32 v135, 0, v199, vcc
	v_cmp_eq_u32_e32 vcc, 16, v204
	s_nop 1
	v_cndmask_b32_e32 v136, 0, v199, vcc
	v_cmp_eq_u32_e32 vcc, 17, v204
	s_nop 1
	v_cndmask_b32_e32 v137, 0, v199, vcc
	v_cmp_eq_u32_e32 vcc, 18, v204
	s_nop 1
	v_cndmask_b32_e32 v138, 0, v199, vcc
	v_cmp_eq_u32_e32 vcc, 19, v204
	s_nop 1
	v_cndmask_b32_e32 v139, 0, v199, vcc
	v_cmp_eq_u32_e32 vcc, 24, v204
	s_nop 1
	v_cndmask_b32_e32 v140, 0, v199, vcc
	v_cmp_eq_u32_e32 vcc, 25, v204
	s_nop 1
	v_cndmask_b32_e32 v141, 0, v199, vcc
	v_cmp_eq_u32_e32 vcc, 26, v204
	s_nop 1
	v_cndmask_b32_e32 v142, 0, v199, vcc
	v_cmp_eq_u32_e32 vcc, 27, v204
	s_nop 1
	v_cndmask_b32_e32 v143, 0, v199, vcc
	v_mov_b32_e32 v144, 0
	v_mov_b32_e32 v145, 0
	v_mov_b32_e32 v146, 0
	v_mov_b32_e32 v147, 0
	v_mov_b32_e32 v148, 0
	v_mov_b32_e32 v149, 0
	v_mov_b32_e32 v150, 0
	v_mov_b32_e32 v151, 0
	v_mov_b32_e32 v152, 0
	v_mov_b32_e32 v153, 0
	v_mov_b32_e32 v154, 0
	v_mov_b32_e32 v155, 0
	v_mov_b32_e32 v156, 0
	v_mov_b32_e32 v157, 0
	v_mov_b32_e32 v158, 0
	v_mov_b32_e32 v159, 0
	v_mov_b32_e32 v160, 0
	v_mov_b32_e32 v161, 0
	v_mov_b32_e32 v162, 0
	v_mov_b32_e32 v163, 0
	v_mov_b32_e32 v164, 0
	v_mov_b32_e32 v165, 0
	v_mov_b32_e32 v166, 0
	v_mov_b32_e32 v167, 0
	v_mov_b32_e32 v168, 0
	v_mov_b32_e32 v169, 0
	v_mov_b32_e32 v170, 0
	v_mov_b32_e32 v171, 0
	v_mov_b32_e32 v172, 0
	v_mov_b32_e32 v173, 0
	v_mov_b32_e32 v174, 0
	v_mov_b32_e32 v175, 0
	v_cmp_eq_u32_e32 vcc, 0, v204
	s_nop 1
	v_cndmask_b32_e32 v176, 0, v199, vcc
	v_cmp_eq_u32_e32 vcc, 1, v204
	s_nop 1
	v_cndmask_b32_e32 v177, 0, v199, vcc
	v_cmp_eq_u32_e32 vcc, 2, v204
	s_nop 1
	v_cndmask_b32_e32 v178, 0, v199, vcc
	v_cmp_eq_u32_e32 vcc, 3, v204
	s_nop 1
	v_cndmask_b32_e32 v179, 0, v199, vcc
	v_cmp_eq_u32_e32 vcc, 8, v204
	s_nop 1
	v_cndmask_b32_e32 v180, 0, v199, vcc
	v_cmp_eq_u32_e32 vcc, 9, v204
	s_nop 1
	v_cndmask_b32_e32 v181, 0, v199, vcc
	v_cmp_eq_u32_e32 vcc, 10, v204
	s_nop 1
	v_cndmask_b32_e32 v182, 0, v199, vcc
	v_cmp_eq_u32_e32 vcc, 11, v204
	s_nop 1
	v_cndmask_b32_e32 v183, 0, v199, vcc
	v_cmp_eq_u32_e32 vcc, 16, v204
	s_nop 1
	v_cndmask_b32_e32 v184, 0, v199, vcc
	v_cmp_eq_u32_e32 vcc, 17, v204
	s_nop 1
	v_cndmask_b32_e32 v185, 0, v199, vcc
	v_cmp_eq_u32_e32 vcc, 18, v204
	s_nop 1
	v_cndmask_b32_e32 v186, 0, v199, vcc
	v_cmp_eq_u32_e32 vcc, 19, v204
	s_nop 1
	v_cndmask_b32_e32 v187, 0, v199, vcc
	v_cmp_eq_u32_e32 vcc, 24, v204
	s_nop 1
	v_cndmask_b32_e32 v188, 0, v199, vcc
	v_cmp_eq_u32_e32 vcc, 25, v204
	s_nop 1
	v_cndmask_b32_e32 v189, 0, v199, vcc
	v_cmp_eq_u32_e32 vcc, 26, v204
	s_nop 1
	v_cndmask_b32_e32 v190, 0, v199, vcc
	v_cmp_eq_u32_e32 vcc, 27, v204
	s_nop 1
	v_cndmask_b32_e32 v191, 0, v199, vcc
	s_waitcnt vmcnt(0)
; #define LAS __attribute__((address_space(3)))
; __device__ __forceinline__ float bflo(unsigned u) { return __uint_as_float(u << 16); }
; __device__ __forceinline__ float bfhi(unsigned u) { return __uint_as_float(u & 0xffff0000u); }
; template <int NV, bool WITH_Y, int CH>
; __device__ __forceinline__ void scan_run(f32x2 (&S)[4][8], const unsigned char* oh  , LAS float* wl, float* yout  , int lane) {
;     ...
; #pragma unroll
;         for (int st = 0; st < CH; ++st) {
;             const u32x4 u = pa[st];
;             const f32x4 lo = isw ? __builtin_bit_cast(f32x4, u) : (f32x4){bflo(u.x), bfhi(u.x), bflo(u.y), bfhi(u.y)};
;             if (act) *(LAS f32x4*)(l0 + st * 384) = lo;
;             if (act && !isw) *(LAS f32x4*)(l0 + st * 384 + 4) = (f32x4){bflo(u.z), bfhi(u.z), bflo(u.w), bfhi(u.w)};
;         }
;         asm volatile("s_waitcnt lgkmcnt(0)" ::: "memory");
;         if (c + 1 < SEGLEN / CH) {
;             const unsigned char* n0 = g0 + (size_t)(c + 1) * CH * OPTB;
; #pragma unroll
;             for (int st = 0; st < CH; ++st) pa[st] = *(const u32x4*)(n0 + (size_t)st * OPTB);
;         }
; #pragma unroll 1
;         for (int s = 0; s < CH; ++s) {
;             const LAS float* sp = wl + s * 384 + cs16;
;             f32x4 a4[4], w4[4], b4[4], k4[4], r4[4], v4 = {0.f, 0.f, 0.f, 0.f};
; #pragma unroll
;             for (int q = 0; q < 4; ++q) a4[q] = *(const LAS f32x4*)(sp + q * 4);
; #pragma unroll
;             for (int q = 0; q < 4; ++q) { w4[q] = *(const LAS f32x4*)(sp + 64 + q * 4); b4[q] = *(const LAS f32x4*)(sp + 128 + q * 4); }
;             if (NV >= 5) {
; #pragma unroll
;                 for (int q = 0; q < 4; ++q) k4[q] = *(const LAS f32x4*)(sp + 192 + q * 4);
;                 v4 = *(const LAS f32x4*)(wl + s * 384 + 256 + rg4);
.Lscan_chunk:
	v_cmp_gt_u32_e32 vcc, 16, v106
	v_lshlrev_b32_e32 v28, 16, v12
	v_and_b32_e32 v29, 0xffff0000, v12
	v_lshlrev_b32_e32 v30, 16, v13
	v_and_b32_e32 v31, 0xffff0000, v13
	v_cndmask_b32_e32 v31, v31, v15, vcc
	v_cndmask_b32_e32 v30, v30, v14, vcc
	v_cndmask_b32_e32 v29, v29, v13, vcc
	v_cndmask_b32_e32 v28, v28, v12, vcc
	ds_write_b128 v6, v[28:31] offset:0
	v_lshlrev_b32_e32 v28, 16, v16
	v_and_b32_e32 v29, 0xffff0000, v16
	v_lshlrev_b32_e32 v30, 16, v17
	v_and_b32_e32 v31, 0xffff0000, v17
	v_cndmask_b32_e32 v31, v31, v19, vcc
	v_cndmask_b32_e32 v30, v30, v18, vcc
	v_cndmask_b32_e32 v29, v29, v17, vcc
	v_cndmask_b32_e32 v28, v28, v16, vcc
	ds_write_b128 v6, v[28:31] offset:1536
	v_lshlrev_b32_e32 v28, 16, v20
	v_and_b32_e32 v29, 0xffff0000, v20
	v_lshlrev_b32_e32 v30, 16, v21
	v_and_b32_e32 v31, 0xffff0000, v21
	v_cndmask_b32_e32 v31, v31, v23, vcc
	v_cndmask_b32_e32 v30, v30, v22, vcc
	v_cndmask_b32_e32 v29, v29, v21, vcc
	v_cndmask_b32_e32 v28, v28, v20, vcc
	ds_write_b128 v6, v[28:31] offset:3072
	v_lshlrev_b32_e32 v28, 16, v24
	v_and_b32_e32 v29, 0xffff0000, v24
	v_lshlrev_b32_e32 v30, 16, v25
	v_and_b32_e32 v31, 0xffff0000, v25
	v_cndmask_b32_e32 v31, v31, v27, vcc
	v_cndmask_b32_e32 v30, v30, v26, vcc
	v_cndmask_b32_e32 v29, v29, v25, vcc
	v_cndmask_b32_e32 v28, v28, v24, vcc
	ds_write_b128 v6, v[28:31] offset:4608
	v_cmp_lt_u32_e64 s[4:5], 15, v106
	s_nop 1
	s_mov_b64 exec, s[4:5]
	v_lshlrev_b32_e32 v28, 16, v14
	v_and_b32_e32 v29, 0xffff0000, v14
	v_lshlrev_b32_e32 v30, 16, v15
	v_and_b32_e32 v31, 0xffff0000, v15
	ds_write_b128 v6, v[28:31] offset:16
	v_lshlrev_b32_e32 v28, 16, v18
	v_and_b32_e32 v29, 0xffff0000, v18
	v_lshlrev_b32_e32 v30, 16, v19
	v_and_b32_e32 v31, 0xffff0000, v19
	ds_write_b128 v6, v[28:31] offset:1552
	v_lshlrev_b32_e32 v28, 16, v22
	v_and_b32_e32 v29, 0xffff0000, v22
	v_lshlrev_b32_e32 v30, 16, v23
	v_and_b32_e32 v31, 0xffff0000, v23
	ds_write_b128 v6, v[28:31] offset:3088
	v_lshlrev_b32_e32 v28, 16, v26
	v_and_b32_e32 v29, 0xffff0000, v26
	v_lshlrev_b32_e32 v30, 16, v27
	v_and_b32_e32 v31, 0xffff0000, v27
	ds_write_b128 v6, v[28:31] offset:4624
	s_mov_b64 exec, -1
	s_waitcnt lgkmcnt(0)
	s_cmp_eq_u32 s51, 15
	s_cbranch_scc1 .Lscan_noload
	s_add_i32 s10, s51, 1
	s_mul_i32 s10, s10, 0xa800
	v_lshl_add_u64 v[32:33], v[4:5], 0, s[10:11]
	v_add_co_u32_e32 v34, vcc, s71, v32
	s_nop 1
	v_addc_co_u32_e32 v35, vcc, 0, v33, vcc
	global_load_dwordx4 v[12:15], v[32:33], off
	global_load_dwordx4 v[16:19], v[34:35], off offset:2560
	v_add_co_u32_e32 v34, vcc, 0x5000, v32
	s_nop 1
	v_addc_co_u32_e32 v35, vcc, 0, v33, vcc
	global_load_dwordx4 v[20:23], v[34:35], off offset:1024
	v_add_co_u32_e32 v34, vcc, 0x7000, v32
	s_nop 1
	v_addc_co_u32_e32 v35, vcc, 0, v33, vcc
	global_load_dwordx4 v[24:27], v[34:35], off offset:3584
.Lscan_noload:
	ds_read_b128 v[64:67], v7 offset:0
	ds_read_b128 v[56:59], v7 offset:256
	ds_read_b128 v[68:71], v7 offset:32
	ds_read_b128 v[60:63], v7 offset:288
	ds_read_b128 v[72:75], v7 offset:64
	ds_read_b128 v[212:215], v7 offset:320
	ds_read_b128 v[76:79], v7 offset:96
	ds_read_b128 v[216:219], v7 offset:352
	ds_read_b128 v[80:83], v7 offset:128
	ds_read_b128 v[220:223], v7 offset:384
	ds_read_b128 v[84:87], v7 offset:160
	ds_read_b128 v[224:227], v7 offset:416
	ds_read_b128 v[88:91], v7 offset:192
	ds_read_b128 v[228:231], v7 offset:448
	ds_read_b128 v[92:95], v7 offset:224
	ds_read_b128 v[232:235], v7 offset:480
	ds_read_b32 v38, v8 offset:512
	ds_read_b32 v39, v8 offset:640
	ds_read_b32 v36, v9 offset:1024
	s_waitcnt lgkmcnt(0)
	v_pk_mul_f32 v[42:43], v[128:129], v[64:65]
	v_pk_mul_f32 v[128:129], v[128:129], v[56:57]
	v_pk_mul_f32 v[44:45], v[144:145], v[64:65]
	v_pk_mul_f32 v[144:145], v[144:145], v[56:57]
	v_pk_fma_f32 v[42:43], v[130:131], v[66:67], v[42:43]
	v_pk_mul_f32 v[130:131], v[130:131], v[58:59]
	v_pk_fma_f32 v[44:45], v[146:147], v[66:67], v[44:45]
	v_pk_mul_f32 v[146:147], v[146:147], v[58:59]
	v_pk_fma_f32 v[42:43], v[132:133], v[68:69], v[42:43]
	v_pk_mul_f32 v[132:133], v[132:133], v[60:61]
	v_pk_fma_f32 v[44:45], v[148:149], v[68:69], v[44:45]
	v_pk_mul_f32 v[148:149], v[148:149], v[60:61]
	v_pk_fma_f32 v[42:43], v[134:135], v[70:71], v[42:43]
	v_pk_mul_f32 v[134:135], v[134:135], v[62:63]
	v_pk_fma_f32 v[44:45], v[150:151], v[70:71], v[44:45]
	v_pk_mul_f32 v[150:151], v[150:151], v[62:63]
	v_pk_fma_f32 v[42:43], v[136:137], v[72:73], v[42:43]
	v_pk_mul_f32 v[136:137], v[136:137], v[212:213]
	v_pk_fma_f32 v[44:45], v[152:153], v[72:73], v[44:45]
	v_pk_mul_f32 v[152:153], v[152:153], v[212:213]
	v_pk_fma_f32 v[42:43], v[138:139], v[74:75], v[42:43]
	v_pk_mul_f32 v[138:139], v[138:139], v[214:215]
	v_pk_fma_f32 v[44:45], v[154:155], v[74:75], v[44:45]
	v_pk_mul_f32 v[154:155], v[154:155], v[214:215]
	v_pk_fma_f32 v[42:43], v[140:141], v[76:77], v[42:43]
	v_pk_mul_f32 v[140:141], v[140:141], v[216:217]
	v_pk_fma_f32 v[44:45], v[156:157], v[76:77], v[44:45]
	v_pk_mul_f32 v[156:157], v[156:157], v[216:217]
	v_pk_fma_f32 v[42:43], v[142:143], v[78:79], v[42:43]
	v_pk_mul_f32 v[142:143], v[142:143], v[218:219]
	v_pk_fma_f32 v[44:45], v[158:159], v[78:79], v[44:45]
	v_pk_mul_f32 v[158:159], v[158:159], v[218:219]
	v_pk_fma_f32 v[42:43], v[160:161], v[80:81], v[42:43]
	v_pk_mul_f32 v[160:161], v[160:161], v[220:221]
	v_pk_fma_f32 v[44:45], v[176:177], v[80:81], v[44:45]
	v_pk_mul_f32 v[176:177], v[176:177], v[220:221]
	v_pk_fma_f32 v[42:43], v[162:163], v[82:83], v[42:43]
	v_pk_mul_f32 v[162:163], v[162:163], v[222:223]
	v_pk_fma_f32 v[44:45], v[178:179], v[82:83], v[44:45]
	v_pk_mul_f32 v[178:179], v[178:179], v[222:223]
	v_pk_fma_f32 v[42:43], v[164:165], v[84:85], v[42:43]
; template <int NV, bool WITH_Y, int CH>
; __device__ __forceinline__ void scan_run(f32x2 (&S)[4][8], const unsigned char* oh  , LAS float* wl, float* yout  , int lane) {
;     ...
;             __builtin_amdgcn_sched_barrier(0);
;             float sa[4];
; #pragma unroll
;             for (int r = 0; r < 4; ++r) {
;                 f32x2 e0 = S[r][0] * (f32x2){a4[0][0], a4[0][1]}, e1 = S[r][1] * (f32x2){a4[0][2], a4[0][3]};
; #pragma unroll
;                 for (int q = 1; q < 4; ++q) { e0 += S[r][2 * q] * (f32x2){a4[q][0], a4[q][1]}; e1 += S[r][2 * q + 1] * (f32x2){a4[q][2], a4[q][3]}; }
;                 sa[r] = quad_allsum((e0[0] + e0[1]) + (e1[0] + e1[1]));
;             }
; #pragma unroll
;             for (int q = 0; q < 4; ++q) {
;                 const f32x2 wlo = {w4[q][0], w4[q][1]}, whi = {w4[q][2], w4[q][3]}, blo = {b4[q][0], b4[q][1]}, bhi = {b4[q][2], b4[q][3]};
;                 if (NV >= 5) {
;                     const f32x2 klo = {k4[q][0], k4[q][1]}, khi = {k4[q][2], k4[q][3]};
; #pragma unroll
;                     for (int r = 0; r < 4; ++r) {
;                         const f32x2 sa2 = {sa[r], sa[r]}, vi2 = {v4[r], v4[r]};
;                         S[r][2 * q] = S[r][2 * q] * wlo + (blo * sa2 + klo * vi2);
;                         S[r][2 * q + 1] = S[r][2 * q + 1] * whi + (bhi * sa2 + khi * vi2);
;                     }
;                 } else {
; #pragma unroll
;                     for (int r = 0; r < 4; ++r) {
;                         const f32x2 sa2 = {sa[r], sa[r]};
;                         S[r][2 * q] = S[r][2 * q] * wlo + blo * sa2;
;                         S[r][2 * q + 1] = S[r][2 * q + 1] * whi + bhi * sa2;
;                     }
;                 }
;             }
;             if (WITH_Y) {
;                 float y[4];
; #pragma unroll
;                 for (int r = 0; r < 4; ++r) {
;                     f32x2 e0 = S[r][0] * (f32x2){r4[0][0], r4[0][1]}, e1 = S[r][1] * (f32x2){r4[0][2], r4[0][3]};
; #pragma unroll
;                     for (int q = 1; q < 4; ++q) { e0 += S[r][2 * q] * (f32x2){r4[q][0], r4[q][1]}; e1 += S[r][2 * q + 1] * (f32x2){r4[q][2], r4[q][3]}; }
;                     y[r] = quad_allsum((e0[0] + e0[1]) + (e1[0] + e1[1]));
;                 }
;                 const int cs = lane & 3;
;                 const float ysel = cs == 0 ? y[0] : (cs == 1 ? y[1] : (cs == 2 ? y[2] : y[3]));
	v_pk_mul_f32 v[164:165], v[164:165], v[224:225]
	v_pk_fma_f32 v[44:45], v[180:181], v[84:85], v[44:45]
	v_pk_mul_f32 v[180:181], v[180:181], v[224:225]
	v_pk_fma_f32 v[42:43], v[166:167], v[86:87], v[42:43]
	v_pk_mul_f32 v[166:167], v[166:167], v[226:227]
	v_pk_fma_f32 v[44:45], v[182:183], v[86:87], v[44:45]
	v_pk_mul_f32 v[182:183], v[182:183], v[226:227]
	v_pk_fma_f32 v[42:43], v[168:169], v[88:89], v[42:43]
	v_pk_mul_f32 v[168:169], v[168:169], v[228:229]
	v_pk_fma_f32 v[44:45], v[184:185], v[88:89], v[44:45]
	v_pk_mul_f32 v[184:185], v[184:185], v[228:229]
	v_pk_fma_f32 v[42:43], v[170:171], v[90:91], v[42:43]
	v_pk_mul_f32 v[170:171], v[170:171], v[230:231]
	v_pk_fma_f32 v[44:45], v[186:187], v[90:91], v[44:45]
	v_pk_mul_f32 v[186:187], v[186:187], v[230:231]
	v_pk_fma_f32 v[42:43], v[172:173], v[92:93], v[42:43]
	v_pk_mul_f32 v[172:173], v[172:173], v[232:233]
	v_pk_fma_f32 v[44:45], v[188:189], v[92:93], v[44:45]
	v_pk_mul_f32 v[188:189], v[188:189], v[232:233]
	v_pk_fma_f32 v[42:43], v[174:175], v[94:95], v[42:43]
	v_pk_mul_f32 v[174:175], v[174:175], v[234:235]
	v_pk_fma_f32 v[44:45], v[190:191], v[94:95], v[44:45]
	v_pk_mul_f32 v[190:191], v[190:191], v[234:235]
	v_add_f32_e32 v50, v42, v43
	v_add_f32_e32 v51, v44, v45
	v_mul_f32_e32 v36, s36, v36
	s_nop 0
	v_permlane32_swap_b32_e32 v50, v51
	v_add_f32_e32 v52, v50, v51
	s_nop 1
	v_permlane32_swap_b32_e32 v52, v36
	s_nop 1
	v_mfma_f32_32x32x2_f32 v[128:143], v38, v52, v[128:143]
	ds_read_b128 v[64:67], v7 offset:1536
	ds_read_b128 v[56:59], v7 offset:1792
	ds_read_b128 v[68:71], v7 offset:1568
	ds_read_b128 v[60:63], v7 offset:1824
	ds_read_b128 v[72:75], v7 offset:1600
	ds_read_b128 v[212:215], v7 offset:1856
	ds_read_b128 v[76:79], v7 offset:1632
	ds_read_b128 v[216:219], v7 offset:1888
	ds_read_b128 v[80:83], v7 offset:1664
	v_mfma_f32_32x32x2_f32 v[144:159], v38, v36, v[144:159]
	ds_read_b128 v[220:223], v7 offset:1920
	ds_read_b128 v[84:87], v7 offset:1696
	ds_read_b128 v[224:227], v7 offset:1952
	ds_read_b128 v[88:91], v7 offset:1728
	ds_read_b128 v[228:231], v7 offset:1984
	ds_read_b128 v[92:95], v7 offset:1760
	ds_read_b128 v[232:235], v7 offset:2016
	ds_read_b32 v40, v8 offset:2048
	ds_read_b32 v41, v8 offset:2176
	v_mfma_f32_32x32x2_f32 v[160:175], v39, v52, v[160:175]
	ds_read_b32 v37, v9 offset:2560
	ds_read_b128 v[96:99], v7 offset:1280
	ds_read_b128 v[100:103], v7 offset:1312
	ds_read_b128 v[108:111], v7 offset:1344
	ds_read_b128 v[112:115], v7 offset:1376
	ds_read_b128 v[116:119], v7 offset:1408
	ds_read_b128 v[120:123], v7 offset:1440
	ds_read_b128 v[124:127], v7 offset:1472
	ds_read_b128 v[192:195], v7 offset:1504
	v_mfma_f32_32x32x2_f32 v[176:191], v39, v36, v[176:191]
	s_waitcnt lgkmcnt(0)
	v_pk_mul_f32 v[42:43], v[128:129], v[64:65]
	v_pk_mul_f32 v[46:47], v[128:129], v[96:97]
	v_pk_mul_f32 v[128:129], v[128:129], v[56:57]
	v_pk_mul_f32 v[44:45], v[144:145], v[64:65]
	v_pk_mul_f32 v[48:49], v[144:145], v[96:97]
	v_pk_mul_f32 v[144:145], v[144:145], v[56:57]
	v_pk_fma_f32 v[42:43], v[130:131], v[66:67], v[42:43]
	v_pk_fma_f32 v[46:47], v[130:131], v[98:99], v[46:47]
	v_pk_mul_f32 v[130:131], v[130:131], v[58:59]
	v_pk_fma_f32 v[44:45], v[146:147], v[66:67], v[44:45]
	v_pk_fma_f32 v[48:49], v[146:147], v[98:99], v[48:49]
	v_pk_mul_f32 v[146:147], v[146:147], v[58:59]
	v_pk_fma_f32 v[42:43], v[132:133], v[68:69], v[42:43]
	v_pk_fma_f32 v[46:47], v[132:133], v[100:101], v[46:47]
	v_pk_mul_f32 v[132:133], v[132:133], v[60:61]
	v_pk_fma_f32 v[44:45], v[148:149], v[68:69], v[44:45]
	v_pk_fma_f32 v[48:49], v[148:149], v[100:101], v[48:49]
	v_pk_mul_f32 v[148:149], v[148:149], v[60:61]
	v_pk_fma_f32 v[42:43], v[134:135], v[70:71], v[42:43]
	v_pk_fma_f32 v[46:47], v[134:135], v[102:103], v[46:47]
	v_pk_mul_f32 v[134:135], v[134:135], v[62:63]
	v_pk_fma_f32 v[44:45], v[150:151], v[70:71], v[44:45]
	v_pk_fma_f32 v[48:49], v[150:151], v[102:103], v[48:49]
	v_pk_mul_f32 v[150:151], v[150:151], v[62:63]
	v_pk_fma_f32 v[42:43], v[136:137], v[72:73], v[42:43]
	v_pk_fma_f32 v[46:47], v[136:137], v[108:109], v[46:47]
	v_pk_mul_f32 v[136:137], v[136:137], v[212:213]
	v_pk_fma_f32 v[44:45], v[152:153], v[72:73], v[44:45]
	v_pk_fma_f32 v[48:49], v[152:153], v[108:109], v[48:49]
	v_pk_mul_f32 v[152:153], v[152:153], v[212:213]
	v_pk_fma_f32 v[42:43], v[138:139], v[74:75], v[42:43]
	v_pk_fma_f32 v[46:47], v[138:139], v[110:111], v[46:47]
	v_pk_mul_f32 v[138:139], v[138:139], v[214:215]
	v_pk_fma_f32 v[44:45], v[154:155], v[74:75], v[44:45]
	v_pk_fma_f32 v[48:49], v[154:155], v[110:111], v[48:49]
	v_pk_mul_f32 v[154:155], v[154:155], v[214:215]
	v_pk_fma_f32 v[42:43], v[140:141], v[76:77], v[42:43]
	v_pk_fma_f32 v[46:47], v[140:141], v[112:113], v[46:47]
	v_pk_mul_f32 v[140:141], v[140:141], v[216:217]
	v_pk_fma_f32 v[44:45], v[156:157], v[76:77], v[44:45]
	v_pk_fma_f32 v[48:49], v[156:157], v[112:113], v[48:49]
	v_pk_mul_f32 v[156:157], v[156:157], v[216:217]
	v_pk_fma_f32 v[42:43], v[142:143], v[78:79], v[42:43]
	v_pk_fma_f32 v[46:47], v[142:143], v[114:115], v[46:47]
	v_pk_mul_f32 v[142:143], v[142:143], v[218:219]
	v_pk_fma_f32 v[44:45], v[158:159], v[78:79], v[44:45]
	v_pk_fma_f32 v[48:49], v[158:159], v[114:115], v[48:49]
	v_pk_mul_f32 v[158:159], v[158:159], v[218:219]
	v_pk_fma_f32 v[42:43], v[160:161], v[80:81], v[42:43]
	v_pk_fma_f32 v[46:47], v[160:161], v[116:117], v[46:47]
	v_pk_mul_f32 v[160:161], v[160:161], v[220:221]
	v_pk_fma_f32 v[44:45], v[176:177], v[80:81], v[44:45]
	v_pk_fma_f32 v[48:49], v[176:177], v[116:117], v[48:49]
	v_pk_mul_f32 v[176:177], v[176:177], v[220:221]
	v_pk_fma_f32 v[42:43], v[162:163], v[82:83], v[42:43]
	v_pk_fma_f32 v[46:47], v[162:163], v[118:119], v[46:47]
; template <int NV, bool WITH_Y, int CH>
; __device__ __forceinline__ void scan_run(f32x2 (&S)[4][8], const unsigned char* oh  , LAS float* wl, float* yout  , int lane) {
;     ...
;             __builtin_amdgcn_sched_barrier(0);
;             float sa[4];
; #pragma unroll
;             for (int r = 0; r < 4; ++r) {
;                 f32x2 e0 = S[r][0] * (f32x2){a4[0][0], a4[0][1]}, e1 = S[r][1] * (f32x2){a4[0][2], a4[0][3]};
; #pragma unroll
;                 for (int q = 1; q < 4; ++q) { e0 += S[r][2 * q] * (f32x2){a4[q][0], a4[q][1]}; e1 += S[r][2 * q + 1] * (f32x2){a4[q][2], a4[q][3]}; }
;                 sa[r] = quad_allsum((e0[0] + e0[1]) + (e1[0] + e1[1]));
;             }
; #pragma unroll
;             for (int q = 0; q < 4; ++q) {
;                 const f32x2 wlo = {w4[q][0], w4[q][1]}, whi = {w4[q][2], w4[q][3]}, blo = {b4[q][0], b4[q][1]}, bhi = {b4[q][2], b4[q][3]};
;                 if (NV >= 5) {
;                     const f32x2 klo = {k4[q][0], k4[q][1]}, khi = {k4[q][2], k4[q][3]};
; #pragma unroll
;                     for (int r = 0; r < 4; ++r) {
;                         const f32x2 sa2 = {sa[r], sa[r]}, vi2 = {v4[r], v4[r]};
;                         S[r][2 * q] = S[r][2 * q] * wlo + (blo * sa2 + klo * vi2);
;                         S[r][2 * q + 1] = S[r][2 * q + 1] * whi + (bhi * sa2 + khi * vi2);
;                     }
;                 } else {
; #pragma unroll
;                     for (int r = 0; r < 4; ++r) {
;                         const f32x2 sa2 = {sa[r], sa[r]};
;                         S[r][2 * q] = S[r][2 * q] * wlo + blo * sa2;
;                         S[r][2 * q + 1] = S[r][2 * q + 1] * whi + bhi * sa2;
;                     }
;                 }
;             }
;             if (WITH_Y) {
;                 float y[4];
; #pragma unroll
;                 for (int r = 0; r < 4; ++r) {
;                     f32x2 e0 = S[r][0] * (f32x2){r4[0][0], r4[0][1]}, e1 = S[r][1] * (f32x2){r4[0][2], r4[0][3]};
; #pragma unroll
;                     for (int q = 1; q < 4; ++q) { e0 += S[r][2 * q] * (f32x2){r4[q][0], r4[q][1]}; e1 += S[r][2 * q + 1] * (f32x2){r4[q][2], r4[q][3]}; }
;                     y[r] = quad_allsum((e0[0] + e0[1]) + (e1[0] + e1[1]));
;                 }
;                 const int cs = lane & 3;
;                 const float ysel = cs == 0 ? y[0] : (cs == 1 ? y[1] : (cs == 2 ? y[2] : y[3]));
	v_pk_mul_f32 v[162:163], v[162:163], v[222:223]
	v_pk_fma_f32 v[44:45], v[178:179], v[82:83], v[44:45]
	v_pk_fma_f32 v[48:49], v[178:179], v[118:119], v[48:49]
	v_pk_mul_f32 v[178:179], v[178:179], v[222:223]
	v_pk_fma_f32 v[42:43], v[164:165], v[84:85], v[42:43]
	v_pk_fma_f32 v[46:47], v[164:165], v[120:121], v[46:47]
	v_pk_mul_f32 v[164:165], v[164:165], v[224:225]
	v_pk_fma_f32 v[44:45], v[180:181], v[84:85], v[44:45]
	v_pk_fma_f32 v[48:49], v[180:181], v[120:121], v[48:49]
	v_pk_mul_f32 v[180:181], v[180:181], v[224:225]
	v_pk_fma_f32 v[42:43], v[166:167], v[86:87], v[42:43]
	v_pk_fma_f32 v[46:47], v[166:167], v[122:123], v[46:47]
	v_pk_mul_f32 v[166:167], v[166:167], v[226:227]
	v_pk_fma_f32 v[44:45], v[182:183], v[86:87], v[44:45]
	v_pk_fma_f32 v[48:49], v[182:183], v[122:123], v[48:49]
	v_pk_mul_f32 v[182:183], v[182:183], v[226:227]
	v_pk_fma_f32 v[42:43], v[168:169], v[88:89], v[42:43]
	v_pk_fma_f32 v[46:47], v[168:169], v[124:125], v[46:47]
	v_pk_mul_f32 v[168:169], v[168:169], v[228:229]
	v_pk_fma_f32 v[44:45], v[184:185], v[88:89], v[44:45]
	v_pk_fma_f32 v[48:49], v[184:185], v[124:125], v[48:49]
	v_pk_mul_f32 v[184:185], v[184:185], v[228:229]
	v_pk_fma_f32 v[42:43], v[170:171], v[90:91], v[42:43]
	v_pk_fma_f32 v[46:47], v[170:171], v[126:127], v[46:47]
	v_pk_mul_f32 v[170:171], v[170:171], v[230:231]
	v_pk_fma_f32 v[44:45], v[186:187], v[90:91], v[44:45]
	v_pk_fma_f32 v[48:49], v[186:187], v[126:127], v[48:49]
	v_pk_mul_f32 v[186:187], v[186:187], v[230:231]
	v_pk_fma_f32 v[42:43], v[172:173], v[92:93], v[42:43]
	v_pk_fma_f32 v[46:47], v[172:173], v[192:193], v[46:47]
	v_pk_mul_f32 v[172:173], v[172:173], v[232:233]
	v_pk_fma_f32 v[44:45], v[188:189], v[92:93], v[44:45]
	v_pk_fma_f32 v[48:49], v[188:189], v[192:193], v[48:49]
	v_pk_mul_f32 v[188:189], v[188:189], v[232:233]
	v_pk_fma_f32 v[42:43], v[174:175], v[94:95], v[42:43]
	v_pk_fma_f32 v[46:47], v[174:175], v[194:195], v[46:47]
	v_pk_mul_f32 v[174:175], v[174:175], v[234:235]
	v_pk_fma_f32 v[44:45], v[190:191], v[94:95], v[44:45]
	v_pk_fma_f32 v[48:49], v[190:191], v[194:195], v[48:49]
	v_pk_mul_f32 v[190:191], v[190:191], v[234:235]
	v_add_f32_e32 v50, v42, v43
	v_add_f32_e32 v51, v44, v45
	v_add_f32_e32 v54, v46, v47
	v_add_f32_e32 v55, v48, v49
	v_mul_f32_e32 v37, s36, v37
	v_permlane32_swap_b32_e32 v50, v51
	v_permlane32_swap_b32_e32 v54, v55
	v_add_f32_e32 v53, v50, v51
	v_add_f32_e32 v198, v54, v55
	s_nop 0
	v_permlane32_swap_b32_e32 v53, v37
	global_store_dword v[10:11], v198, off
	v_lshl_add_u64 v[10:11], v[10:11], 0, s[92:93]
	v_mfma_f32_32x32x2_f32 v[128:143], v40, v53, v[128:143]
	ds_read_b128 v[64:67], v7 offset:3072
	ds_read_b128 v[56:59], v7 offset:3328
	ds_read_b128 v[68:71], v7 offset:3104
	ds_read_b128 v[60:63], v7 offset:3360
	ds_read_b128 v[72:75], v7 offset:3136
	ds_read_b128 v[212:215], v7 offset:3392
	ds_read_b128 v[76:79], v7 offset:3168
	ds_read_b128 v[216:219], v7 offset:3424
	ds_read_b128 v[80:83], v7 offset:3200
	v_mfma_f32_32x32x2_f32 v[144:159], v40, v37, v[144:159]
	ds_read_b128 v[220:223], v7 offset:3456
	ds_read_b128 v[84:87], v7 offset:3232
	ds_read_b128 v[224:227], v7 offset:3488
	ds_read_b128 v[88:91], v7 offset:3264
	ds_read_b128 v[228:231], v7 offset:3520
	ds_read_b128 v[92:95], v7 offset:3296
	ds_read_b128 v[232:235], v7 offset:3552
	ds_read_b32 v38, v8 offset:3584
	ds_read_b32 v39, v8 offset:3712
	v_mfma_f32_32x32x2_f32 v[160:175], v41, v53, v[160:175]
	ds_read_b32 v36, v9 offset:4096
	ds_read_b128 v[96:99], v7 offset:2816
	ds_read_b128 v[100:103], v7 offset:2848
	ds_read_b128 v[108:111], v7 offset:2880
	ds_read_b128 v[112:115], v7 offset:2912
	ds_read_b128 v[116:119], v7 offset:2944
	ds_read_b128 v[120:123], v7 offset:2976
	ds_read_b128 v[124:127], v7 offset:3008
	ds_read_b128 v[192:195], v7 offset:3040
	v_mfma_f32_32x32x2_f32 v[176:191], v41, v37, v[176:191]
	s_waitcnt lgkmcnt(0)
	v_pk_mul_f32 v[42:43], v[128:129], v[64:65]
	v_pk_mul_f32 v[46:47], v[128:129], v[96:97]
	v_pk_mul_f32 v[128:129], v[128:129], v[56:57]
	v_pk_mul_f32 v[44:45], v[144:145], v[64:65]
	v_pk_mul_f32 v[48:49], v[144:145], v[96:97]
	v_pk_mul_f32 v[144:145], v[144:145], v[56:57]
	v_pk_fma_f32 v[42:43], v[130:131], v[66:67], v[42:43]
	v_pk_fma_f32 v[46:47], v[130:131], v[98:99], v[46:47]
	v_pk_mul_f32 v[130:131], v[130:131], v[58:59]
	v_pk_fma_f32 v[44:45], v[146:147], v[66:67], v[44:45]
	v_pk_fma_f32 v[48:49], v[146:147], v[98:99], v[48:49]
	v_pk_mul_f32 v[146:147], v[146:147], v[58:59]
	v_pk_fma_f32 v[42:43], v[132:133], v[68:69], v[42:43]
	v_pk_fma_f32 v[46:47], v[132:133], v[100:101], v[46:47]
	v_pk_mul_f32 v[132:133], v[132:133], v[60:61]
	v_pk_fma_f32 v[44:45], v[148:149], v[68:69], v[44:45]
	v_pk_fma_f32 v[48:49], v[148:149], v[100:101], v[48:49]
	v_pk_mul_f32 v[148:149], v[148:149], v[60:61]
	v_pk_fma_f32 v[42:43], v[134:135], v[70:71], v[42:43]
	v_pk_fma_f32 v[46:47], v[134:135], v[102:103], v[46:47]
	v_pk_mul_f32 v[134:135], v[134:135], v[62:63]
	v_pk_fma_f32 v[44:45], v[150:151], v[70:71], v[44:45]
	v_pk_fma_f32 v[48:49], v[150:151], v[102:103], v[48:49]
	v_pk_mul_f32 v[150:151], v[150:151], v[62:63]
	v_pk_fma_f32 v[42:43], v[136:137], v[72:73], v[42:43]
	v_pk_fma_f32 v[46:47], v[136:137], v[108:109], v[46:47]
	v_pk_mul_f32 v[136:137], v[136:137], v[212:213]
	v_pk_fma_f32 v[44:45], v[152:153], v[72:73], v[44:45]
	v_pk_fma_f32 v[48:49], v[152:153], v[108:109], v[48:49]
	v_pk_mul_f32 v[152:153], v[152:153], v[212:213]
	v_pk_fma_f32 v[42:43], v[138:139], v[74:75], v[42:43]
	v_pk_fma_f32 v[46:47], v[138:139], v[110:111], v[46:47]
	v_pk_mul_f32 v[138:139], v[138:139], v[214:215]
	v_pk_fma_f32 v[44:45], v[154:155], v[74:75], v[44:45]
; template <int NV, bool WITH_Y, int CH>
; __device__ __forceinline__ void scan_run(f32x2 (&S)[4][8], const unsigned char* oh  , LAS float* wl, float* yout  , int lane) {
;     ...
;             __builtin_amdgcn_sched_barrier(0);
;             float sa[4];
; #pragma unroll
;             for (int r = 0; r < 4; ++r) {
;                 f32x2 e0 = S[r][0] * (f32x2){a4[0][0], a4[0][1]}, e1 = S[r][1] * (f32x2){a4[0][2], a4[0][3]};
; #pragma unroll
;                 for (int q = 1; q < 4; ++q) { e0 += S[r][2 * q] * (f32x2){a4[q][0], a4[q][1]}; e1 += S[r][2 * q + 1] * (f32x2){a4[q][2], a4[q][3]}; }
;                 sa[r] = quad_allsum((e0[0] + e0[1]) + (e1[0] + e1[1]));
;             }
; #pragma unroll
;             for (int q = 0; q < 4; ++q) {
;                 const f32x2 wlo = {w4[q][0], w4[q][1]}, whi = {w4[q][2], w4[q][3]}, blo = {b4[q][0], b4[q][1]}, bhi = {b4[q][2], b4[q][3]};
;                 if (NV >= 5) {
;                     const f32x2 klo = {k4[q][0], k4[q][1]}, khi = {k4[q][2], k4[q][3]};
; #pragma unroll
;                     for (int r = 0; r < 4; ++r) {
;                         const f32x2 sa2 = {sa[r], sa[r]}, vi2 = {v4[r], v4[r]};
;                         S[r][2 * q] = S[r][2 * q] * wlo + (blo * sa2 + klo * vi2);
;                         S[r][2 * q + 1] = S[r][2 * q + 1] * whi + (bhi * sa2 + khi * vi2);
;                     }
;                 } else {
; #pragma unroll
;                     for (int r = 0; r < 4; ++r) {
;                         const f32x2 sa2 = {sa[r], sa[r]};
;                         S[r][2 * q] = S[r][2 * q] * wlo + blo * sa2;
;                         S[r][2 * q + 1] = S[r][2 * q + 1] * whi + bhi * sa2;
;                     }
;                 }
;             }
;             if (WITH_Y) {
;                 float y[4];
; #pragma unroll
;                 for (int r = 0; r < 4; ++r) {
;                     f32x2 e0 = S[r][0] * (f32x2){r4[0][0], r4[0][1]}, e1 = S[r][1] * (f32x2){r4[0][2], r4[0][3]};
; #pragma unroll
;                     for (int q = 1; q < 4; ++q) { e0 += S[r][2 * q] * (f32x2){r4[q][0], r4[q][1]}; e1 += S[r][2 * q + 1] * (f32x2){r4[q][2], r4[q][3]}; }
;                     y[r] = quad_allsum((e0[0] + e0[1]) + (e1[0] + e1[1]));
;                 }
;                 const int cs = lane & 3;
;                 const float ysel = cs == 0 ? y[0] : (cs == 1 ? y[1] : (cs == 2 ? y[2] : y[3]));
	v_pk_fma_f32 v[48:49], v[154:155], v[110:111], v[48:49]
	v_pk_mul_f32 v[154:155], v[154:155], v[214:215]
	v_pk_fma_f32 v[42:43], v[140:141], v[76:77], v[42:43]
	v_pk_fma_f32 v[46:47], v[140:141], v[112:113], v[46:47]
	v_pk_mul_f32 v[140:141], v[140:141], v[216:217]
	v_pk_fma_f32 v[44:45], v[156:157], v[76:77], v[44:45]
	v_pk_fma_f32 v[48:49], v[156:157], v[112:113], v[48:49]
	v_pk_mul_f32 v[156:157], v[156:157], v[216:217]
	v_pk_fma_f32 v[42:43], v[142:143], v[78:79], v[42:43]
	v_pk_fma_f32 v[46:47], v[142:143], v[114:115], v[46:47]
	v_pk_mul_f32 v[142:143], v[142:143], v[218:219]
	v_pk_fma_f32 v[44:45], v[158:159], v[78:79], v[44:45]
	v_pk_fma_f32 v[48:49], v[158:159], v[114:115], v[48:49]
	v_pk_mul_f32 v[158:159], v[158:159], v[218:219]
	v_pk_fma_f32 v[42:43], v[160:161], v[80:81], v[42:43]
	v_pk_fma_f32 v[46:47], v[160:161], v[116:117], v[46:47]
	v_pk_mul_f32 v[160:161], v[160:161], v[220:221]
	v_pk_fma_f32 v[44:45], v[176:177], v[80:81], v[44:45]
	v_pk_fma_f32 v[48:49], v[176:177], v[116:117], v[48:49]
	v_pk_mul_f32 v[176:177], v[176:177], v[220:221]
	v_pk_fma_f32 v[42:43], v[162:163], v[82:83], v[42:43]
	v_pk_fma_f32 v[46:47], v[162:163], v[118:119], v[46:47]
	v_pk_mul_f32 v[162:163], v[162:163], v[222:223]
	v_pk_fma_f32 v[44:45], v[178:179], v[82:83], v[44:45]
	v_pk_fma_f32 v[48:49], v[178:179], v[118:119], v[48:49]
	v_pk_mul_f32 v[178:179], v[178:179], v[222:223]
	v_pk_fma_f32 v[42:43], v[164:165], v[84:85], v[42:43]
	v_pk_fma_f32 v[46:47], v[164:165], v[120:121], v[46:47]
	v_pk_mul_f32 v[164:165], v[164:165], v[224:225]
	v_pk_fma_f32 v[44:45], v[180:181], v[84:85], v[44:45]
	v_pk_fma_f32 v[48:49], v[180:181], v[120:121], v[48:49]
	v_pk_mul_f32 v[180:181], v[180:181], v[224:225]
	v_pk_fma_f32 v[42:43], v[166:167], v[86:87], v[42:43]
	v_pk_fma_f32 v[46:47], v[166:167], v[122:123], v[46:47]
	v_pk_mul_f32 v[166:167], v[166:167], v[226:227]
	v_pk_fma_f32 v[44:45], v[182:183], v[86:87], v[44:45]
	v_pk_fma_f32 v[48:49], v[182:183], v[122:123], v[48:49]
	v_pk_mul_f32 v[182:183], v[182:183], v[226:227]
	v_pk_fma_f32 v[42:43], v[168:169], v[88:89], v[42:43]
	v_pk_fma_f32 v[46:47], v[168:169], v[124:125], v[46:47]
	v_pk_mul_f32 v[168:169], v[168:169], v[228:229]
	v_pk_fma_f32 v[44:45], v[184:185], v[88:89], v[44:45]
	v_pk_fma_f32 v[48:49], v[184:185], v[124:125], v[48:49]
	v_pk_mul_f32 v[184:185], v[184:185], v[228:229]
	v_pk_fma_f32 v[42:43], v[170:171], v[90:91], v[42:43]
	v_pk_fma_f32 v[46:47], v[170:171], v[126:127], v[46:47]
	v_pk_mul_f32 v[170:171], v[170:171], v[230:231]
	v_pk_fma_f32 v[44:45], v[186:187], v[90:91], v[44:45]
	v_pk_fma_f32 v[48:49], v[186:187], v[126:127], v[48:49]
	v_pk_mul_f32 v[186:187], v[186:187], v[230:231]
	v_pk_fma_f32 v[42:43], v[172:173], v[92:93], v[42:43]
	v_pk_fma_f32 v[46:47], v[172:173], v[192:193], v[46:47]
	v_pk_mul_f32 v[172:173], v[172:173], v[232:233]
	v_pk_fma_f32 v[44:45], v[188:189], v[92:93], v[44:45]
	v_pk_fma_f32 v[48:49], v[188:189], v[192:193], v[48:49]
	v_pk_mul_f32 v[188:189], v[188:189], v[232:233]
	v_pk_fma_f32 v[42:43], v[174:175], v[94:95], v[42:43]
	v_pk_fma_f32 v[46:47], v[174:175], v[194:195], v[46:47]
	v_pk_mul_f32 v[174:175], v[174:175], v[234:235]
	v_pk_fma_f32 v[44:45], v[190:191], v[94:95], v[44:45]
	v_pk_fma_f32 v[48:49], v[190:191], v[194:195], v[48:49]
	v_pk_mul_f32 v[190:191], v[190:191], v[234:235]
	v_add_f32_e32 v50, v42, v43
	v_add_f32_e32 v51, v44, v45
	v_add_f32_e32 v54, v46, v47
	v_add_f32_e32 v55, v48, v49
	v_mul_f32_e32 v36, s36, v36
	v_permlane32_swap_b32_e32 v50, v51
	v_permlane32_swap_b32_e32 v54, v55
	v_add_f32_e32 v52, v50, v51
	v_add_f32_e32 v198, v54, v55
	s_nop 0
	v_permlane32_swap_b32_e32 v52, v36
	global_store_dword v[10:11], v198, off
	v_lshl_add_u64 v[10:11], v[10:11], 0, s[92:93]
	v_mfma_f32_32x32x2_f32 v[128:143], v38, v52, v[128:143]
	ds_read_b128 v[64:67], v7 offset:4608
	ds_read_b128 v[56:59], v7 offset:4864
	ds_read_b128 v[68:71], v7 offset:4640
	ds_read_b128 v[60:63], v7 offset:4896
	ds_read_b128 v[72:75], v7 offset:4672
	ds_read_b128 v[212:215], v7 offset:4928
	ds_read_b128 v[76:79], v7 offset:4704
	ds_read_b128 v[216:219], v7 offset:4960
	ds_read_b128 v[80:83], v7 offset:4736
	v_mfma_f32_32x32x2_f32 v[144:159], v38, v36, v[144:159]
	ds_read_b128 v[220:223], v7 offset:4992
	ds_read_b128 v[84:87], v7 offset:4768
	ds_read_b128 v[224:227], v7 offset:5024
	ds_read_b128 v[88:91], v7 offset:4800
	ds_read_b128 v[228:231], v7 offset:5056
	ds_read_b128 v[92:95], v7 offset:4832
	ds_read_b128 v[232:235], v7 offset:5088
	ds_read_b32 v40, v8 offset:5120
	ds_read_b32 v41, v8 offset:5248
	v_mfma_f32_32x32x2_f32 v[160:175], v39, v52, v[160:175]
	ds_read_b32 v37, v9 offset:5632
	ds_read_b128 v[96:99], v7 offset:4352
	ds_read_b128 v[100:103], v7 offset:4384
	ds_read_b128 v[108:111], v7 offset:4416
	ds_read_b128 v[112:115], v7 offset:4448
	ds_read_b128 v[116:119], v7 offset:4480
	ds_read_b128 v[120:123], v7 offset:4512
	ds_read_b128 v[124:127], v7 offset:4544
	ds_read_b128 v[192:195], v7 offset:4576
	v_mfma_f32_32x32x2_f32 v[176:191], v39, v36, v[176:191]
	s_waitcnt lgkmcnt(0)
; template <int NV, bool WITH_Y, int CH>
; __device__ __forceinline__ void scan_run(f32x2 (&S)[4][8], const unsigned char* oh  , LAS float* wl, float* yout  , int lane) {
;     ...
;             __builtin_amdgcn_sched_barrier(0);
;             float sa[4];
; #pragma unroll
;             for (int r = 0; r < 4; ++r) {
;                 f32x2 e0 = S[r][0] * (f32x2){a4[0][0], a4[0][1]}, e1 = S[r][1] * (f32x2){a4[0][2], a4[0][3]};
; #pragma unroll
;                 for (int q = 1; q < 4; ++q) { e0 += S[r][2 * q] * (f32x2){a4[q][0], a4[q][1]}; e1 += S[r][2 * q + 1] * (f32x2){a4[q][2], a4[q][3]}; }
;                 sa[r] = quad_allsum((e0[0] + e0[1]) + (e1[0] + e1[1]));
;             }
; #pragma unroll
;             for (int q = 0; q < 4; ++q) {
;                 const f32x2 wlo = {w4[q][0], w4[q][1]}, whi = {w4[q][2], w4[q][3]}, blo = {b4[q][0], b4[q][1]}, bhi = {b4[q][2], b4[q][3]};
;                 if (NV >= 5) {
;                     const f32x2 klo = {k4[q][0], k4[q][1]}, khi = {k4[q][2], k4[q][3]};
; #pragma unroll
;                     for (int r = 0; r < 4; ++r) {
;                         const f32x2 sa2 = {sa[r], sa[r]}, vi2 = {v4[r], v4[r]};
;                         S[r][2 * q] = S[r][2 * q] * wlo + (blo * sa2 + klo * vi2);
;                         S[r][2 * q + 1] = S[r][2 * q + 1] * whi + (bhi * sa2 + khi * vi2);
;                     }
;                 } else {
; #pragma unroll
;                     for (int r = 0; r < 4; ++r) {
;                         const f32x2 sa2 = {sa[r], sa[r]};
;                         S[r][2 * q] = S[r][2 * q] * wlo + blo * sa2;
;                         S[r][2 * q + 1] = S[r][2 * q + 1] * whi + bhi * sa2;
;                     }
;                 }
;             }
;             if (WITH_Y) {
;                 float y[4];
; #pragma unroll
;                 for (int r = 0; r < 4; ++r) {
;                     f32x2 e0 = S[r][0] * (f32x2){r4[0][0], r4[0][1]}, e1 = S[r][1] * (f32x2){r4[0][2], r4[0][3]};
; #pragma unroll
;                     for (int q = 1; q < 4; ++q) { e0 += S[r][2 * q] * (f32x2){r4[q][0], r4[q][1]}; e1 += S[r][2 * q + 1] * (f32x2){r4[q][2], r4[q][3]}; }
;                     y[r] = quad_allsum((e0[0] + e0[1]) + (e1[0] + e1[1]));
;                 }
;                 const int cs = lane & 3;
;                 const float ysel = cs == 0 ? y[0] : (cs == 1 ? y[1] : (cs == 2 ? y[2] : y[3]));
	v_pk_mul_f32 v[42:43], v[128:129], v[64:65]
	v_pk_mul_f32 v[46:47], v[128:129], v[96:97]
	v_pk_mul_f32 v[128:129], v[128:129], v[56:57]
	v_pk_mul_f32 v[44:45], v[144:145], v[64:65]
	v_pk_mul_f32 v[48:49], v[144:145], v[96:97]
	v_pk_mul_f32 v[144:145], v[144:145], v[56:57]
	v_pk_fma_f32 v[42:43], v[130:131], v[66:67], v[42:43]
	v_pk_fma_f32 v[46:47], v[130:131], v[98:99], v[46:47]
	v_pk_mul_f32 v[130:131], v[130:131], v[58:59]
	v_pk_fma_f32 v[44:45], v[146:147], v[66:67], v[44:45]
	v_pk_fma_f32 v[48:49], v[146:147], v[98:99], v[48:49]
	v_pk_mul_f32 v[146:147], v[146:147], v[58:59]
	v_pk_fma_f32 v[42:43], v[132:133], v[68:69], v[42:43]
	v_pk_fma_f32 v[46:47], v[132:133], v[100:101], v[46:47]
	v_pk_mul_f32 v[132:133], v[132:133], v[60:61]
	v_pk_fma_f32 v[44:45], v[148:149], v[68:69], v[44:45]
	v_pk_fma_f32 v[48:49], v[148:149], v[100:101], v[48:49]
	v_pk_mul_f32 v[148:149], v[148:149], v[60:61]
	v_pk_fma_f32 v[42:43], v[134:135], v[70:71], v[42:43]
	v_pk_fma_f32 v[46:47], v[134:135], v[102:103], v[46:47]
	v_pk_mul_f32 v[134:135], v[134:135], v[62:63]
	v_pk_fma_f32 v[44:45], v[150:151], v[70:71], v[44:45]
	v_pk_fma_f32 v[48:49], v[150:151], v[102:103], v[48:49]
	v_pk_mul_f32 v[150:151], v[150:151], v[62:63]
	v_pk_fma_f32 v[42:43], v[136:137], v[72:73], v[42:43]
	v_pk_fma_f32 v[46:47], v[136:137], v[108:109], v[46:47]
	v_pk_mul_f32 v[136:137], v[136:137], v[212:213]
	v_pk_fma_f32 v[44:45], v[152:153], v[72:73], v[44:45]
	v_pk_fma_f32 v[48:49], v[152:153], v[108:109], v[48:49]
	v_pk_mul_f32 v[152:153], v[152:153], v[212:213]
	v_pk_fma_f32 v[42:43], v[138:139], v[74:75], v[42:43]
	v_pk_fma_f32 v[46:47], v[138:139], v[110:111], v[46:47]
	v_pk_mul_f32 v[138:139], v[138:139], v[214:215]
	v_pk_fma_f32 v[44:45], v[154:155], v[74:75], v[44:45]
	v_pk_fma_f32 v[48:49], v[154:155], v[110:111], v[48:49]
	v_pk_mul_f32 v[154:155], v[154:155], v[214:215]
	v_pk_fma_f32 v[42:43], v[140:141], v[76:77], v[42:43]
	v_pk_fma_f32 v[46:47], v[140:141], v[112:113], v[46:47]
	v_pk_mul_f32 v[140:141], v[140:141], v[216:217]
	v_pk_fma_f32 v[44:45], v[156:157], v[76:77], v[44:45]
	v_pk_fma_f32 v[48:49], v[156:157], v[112:113], v[48:49]
	v_pk_mul_f32 v[156:157], v[156:157], v[216:217]
	v_pk_fma_f32 v[42:43], v[142:143], v[78:79], v[42:43]
	v_pk_fma_f32 v[46:47], v[142:143], v[114:115], v[46:47]
	v_pk_mul_f32 v[142:143], v[142:143], v[218:219]
	v_pk_fma_f32 v[44:45], v[158:159], v[78:79], v[44:45]
	v_pk_fma_f32 v[48:49], v[158:159], v[114:115], v[48:49]
	v_pk_mul_f32 v[158:159], v[158:159], v[218:219]
	v_pk_fma_f32 v[42:43], v[160:161], v[80:81], v[42:43]
	v_pk_fma_f32 v[46:47], v[160:161], v[116:117], v[46:47]
	v_pk_mul_f32 v[160:161], v[160:161], v[220:221]
	v_pk_fma_f32 v[44:45], v[176:177], v[80:81], v[44:45]
	v_pk_fma_f32 v[48:49], v[176:177], v[116:117], v[48:49]
	v_pk_mul_f32 v[176:177], v[176:177], v[220:221]
	v_pk_fma_f32 v[42:43], v[162:163], v[82:83], v[42:43]
	v_pk_fma_f32 v[46:47], v[162:163], v[118:119], v[46:47]
	v_pk_mul_f32 v[162:163], v[162:163], v[222:223]
	v_pk_fma_f32 v[44:45], v[178:179], v[82:83], v[44:45]
	v_pk_fma_f32 v[48:49], v[178:179], v[118:119], v[48:49]
	v_pk_mul_f32 v[178:179], v[178:179], v[222:223]
	v_pk_fma_f32 v[42:43], v[164:165], v[84:85], v[42:43]
	v_pk_fma_f32 v[46:47], v[164:165], v[120:121], v[46:47]
	v_pk_mul_f32 v[164:165], v[164:165], v[224:225]
	v_pk_fma_f32 v[44:45], v[180:181], v[84:85], v[44:45]
	v_pk_fma_f32 v[48:49], v[180:181], v[120:121], v[48:49]
	v_pk_mul_f32 v[180:181], v[180:181], v[224:225]
	v_pk_fma_f32 v[42:43], v[166:167], v[86:87], v[42:43]
	v_pk_fma_f32 v[46:47], v[166:167], v[122:123], v[46:47]
	v_pk_mul_f32 v[166:167], v[166:167], v[226:227]
	v_pk_fma_f32 v[44:45], v[182:183], v[86:87], v[44:45]
	v_pk_fma_f32 v[48:49], v[182:183], v[122:123], v[48:49]
	v_pk_mul_f32 v[182:183], v[182:183], v[226:227]
	v_pk_fma_f32 v[42:43], v[168:169], v[88:89], v[42:43]
	v_pk_fma_f32 v[46:47], v[168:169], v[124:125], v[46:47]
	v_pk_mul_f32 v[168:169], v[168:169], v[228:229]
	v_pk_fma_f32 v[44:45], v[184:185], v[88:89], v[44:45]
	v_pk_fma_f32 v[48:49], v[184:185], v[124:125], v[48:49]
	v_pk_mul_f32 v[184:185], v[184:185], v[228:229]
	v_pk_fma_f32 v[42:43], v[170:171], v[90:91], v[42:43]
	v_pk_fma_f32 v[46:47], v[170:171], v[126:127], v[46:47]
	v_pk_mul_f32 v[170:171], v[170:171], v[230:231]
	v_pk_fma_f32 v[44:45], v[186:187], v[90:91], v[44:45]
	v_pk_fma_f32 v[48:49], v[186:187], v[126:127], v[48:49]
	v_pk_mul_f32 v[186:187], v[186:187], v[230:231]
	v_pk_fma_f32 v[42:43], v[172:173], v[92:93], v[42:43]
	v_pk_fma_f32 v[46:47], v[172:173], v[192:193], v[46:47]
	v_pk_mul_f32 v[172:173], v[172:173], v[232:233]
	v_pk_fma_f32 v[44:45], v[188:189], v[92:93], v[44:45]
	v_pk_fma_f32 v[48:49], v[188:189], v[192:193], v[48:49]
	v_pk_mul_f32 v[188:189], v[188:189], v[232:233]
	v_pk_fma_f32 v[42:43], v[174:175], v[94:95], v[42:43]
	v_pk_fma_f32 v[46:47], v[174:175], v[194:195], v[46:47]
	v_pk_mul_f32 v[174:175], v[174:175], v[234:235]
	v_pk_fma_f32 v[44:45], v[190:191], v[94:95], v[44:45]
	v_pk_fma_f32 v[48:49], v[190:191], v[194:195], v[48:49]
	v_pk_mul_f32 v[190:191], v[190:191], v[234:235]
	v_add_f32_e32 v50, v42, v43
	v_add_f32_e32 v51, v44, v45
	v_add_f32_e32 v54, v46, v47
	v_add_f32_e32 v55, v48, v49
	v_mul_f32_e32 v37, s36, v37
	v_permlane32_swap_b32_e32 v50, v51
	v_permlane32_swap_b32_e32 v54, v55
	v_add_f32_e32 v53, v50, v51
	v_add_f32_e32 v198, v54, v55
	s_nop 0
	v_permlane32_swap_b32_e32 v53, v37
	global_store_dword v[10:11], v198, off
	v_lshl_add_u64 v[10:11], v[10:11], 0, s[92:93]
	v_mfma_f32_32x32x2_f32 v[128:143], v40, v53, v[128:143]
	ds_read_b128 v[96:99], v7 offset:5888
	ds_read_b128 v[100:103], v7 offset:5920
	ds_read_b128 v[108:111], v7 offset:5952
	v_mfma_f32_32x32x2_f32 v[144:159], v40, v37, v[144:159]
	ds_read_b128 v[112:115], v7 offset:5984
	ds_read_b128 v[116:119], v7 offset:6016
	ds_read_b128 v[120:123], v7 offset:6048
	v_mfma_f32_32x32x2_f32 v[160:175], v41, v53, v[160:175]
	ds_read_b128 v[124:127], v7 offset:6080
	ds_read_b128 v[192:195], v7 offset:6112
	v_mfma_f32_32x32x2_f32 v[176:191], v41, v37, v[176:191]
	s_nop 15
	s_waitcnt lgkmcnt(0)
; __device__ __forceinline__ float quad_allsum(float v) { v += dpp_mov<0xB1>(v); v += dpp_mov<0x4E>(v); return v; }
; template <int NV, bool WITH_Y, int CH>
; __device__ __forceinline__ void scan_run(f32x2 (&S)[4][8], const unsigned char* oh  , LAS float* wl, float* yout  , int lane) {
;     ...
;             if (WITH_Y) {
;                 float y[4];
; #pragma unroll
;                 for (int r = 0; r < 4; ++r) {
;                     f32x2 e0 = S[r][0] * (f32x2){r4[0][0], r4[0][1]}, e1 = S[r][1] * (f32x2){r4[0][2], r4[0][3]};
; #pragma unroll
;                     for (int q = 1; q < 4; ++q) { e0 += S[r][2 * q] * (f32x2){r4[q][0], r4[q][1]}; e1 += S[r][2 * q + 1] * (f32x2){r4[q][2], r4[q][3]}; }
;                     y[r] = quad_allsum((e0[0] + e0[1]) + (e1[0] + e1[1]));
;                 }
;                 const int cs = lane & 3;
;                 const float ysel = cs == 0 ? y[0] : (cs == 1 ? y[1] : (cs == 2 ? y[2] : y[3]));
;                 yout[(size_t)(c * CH + s) * RW + lane] = ysel;
;             }
;         }
;         asm volatile("s_waitcnt lgkmcnt(0)" ::: "memory");
;     }
; __device__ __forceinline__ void phase_scan1(const Params& p, const Lt& lt, unsigned char* lds) {
;     ...
; #pragma unroll
;         for (int r = 0; r < 4; ++r)
; #pragma unroll
;             for (int q = 0; q < 4; ++q) *(f32x4*)(dst + r * 64 + q * 4) = (f32x4){S[r][2 * q][0], S[r][2 * q][1], S[r][2 * q + 1][0], S[r][2 * q + 1][1]};
	v_pk_mul_f32 v[46:47], v[128:129], v[96:97]
	v_pk_mul_f32 v[42:43], v[144:145], v[96:97]
	v_pk_mul_f32 v[48:49], v[130:131], v[98:99]
	v_pk_mul_f32 v[44:45], v[146:147], v[98:99]
	v_pk_fma_f32 v[46:47], v[132:133], v[100:101], v[46:47]
	v_pk_fma_f32 v[42:43], v[148:149], v[100:101], v[42:43]
	v_pk_fma_f32 v[48:49], v[134:135], v[102:103], v[48:49]
	v_pk_fma_f32 v[44:45], v[150:151], v[102:103], v[44:45]
	v_pk_fma_f32 v[46:47], v[136:137], v[108:109], v[46:47]
	v_pk_fma_f32 v[42:43], v[152:153], v[108:109], v[42:43]
	v_pk_fma_f32 v[48:49], v[138:139], v[110:111], v[48:49]
	v_pk_fma_f32 v[44:45], v[154:155], v[110:111], v[44:45]
	v_pk_fma_f32 v[46:47], v[140:141], v[112:113], v[46:47]
	v_pk_fma_f32 v[42:43], v[156:157], v[112:113], v[42:43]
	v_pk_fma_f32 v[48:49], v[142:143], v[114:115], v[48:49]
	v_pk_fma_f32 v[44:45], v[158:159], v[114:115], v[44:45]
	v_pk_fma_f32 v[46:47], v[160:161], v[116:117], v[46:47]
	v_pk_fma_f32 v[42:43], v[176:177], v[116:117], v[42:43]
	v_pk_fma_f32 v[48:49], v[162:163], v[118:119], v[48:49]
	v_pk_fma_f32 v[44:45], v[178:179], v[118:119], v[44:45]
	v_pk_fma_f32 v[46:47], v[164:165], v[120:121], v[46:47]
	v_pk_fma_f32 v[42:43], v[180:181], v[120:121], v[42:43]
	v_pk_fma_f32 v[48:49], v[166:167], v[122:123], v[48:49]
	v_pk_fma_f32 v[44:45], v[182:183], v[122:123], v[44:45]
	v_pk_fma_f32 v[46:47], v[168:169], v[124:125], v[46:47]
	v_pk_fma_f32 v[42:43], v[184:185], v[124:125], v[42:43]
	v_pk_fma_f32 v[48:49], v[170:171], v[126:127], v[48:49]
	v_pk_fma_f32 v[44:45], v[186:187], v[126:127], v[44:45]
	v_pk_fma_f32 v[46:47], v[172:173], v[192:193], v[46:47]
	v_pk_fma_f32 v[42:43], v[188:189], v[192:193], v[42:43]
	v_pk_fma_f32 v[48:49], v[174:175], v[194:195], v[48:49]
	v_pk_fma_f32 v[44:45], v[190:191], v[194:195], v[44:45]
	v_pk_add_f32 v[46:47], v[46:47], v[48:49]
	v_pk_add_f32 v[42:43], v[42:43], v[44:45]
	s_nop 0
	v_add_f32_e32 v54, v46, v47
	v_add_f32_e32 v55, v42, v43
	s_nop 1
	v_permlane32_swap_b32_e32 v54, v55
	v_add_f32_e32 v198, v54, v55
	global_store_dword v[10:11], v198, off
	v_lshl_add_u64 v[10:11], v[10:11], 0, s[92:93]
	s_add_i32 s51, s51, 1
	s_waitcnt vmcnt(4)
	s_cmp_eq_u32 s51, 16
	s_cbranch_scc0 .Lscan_chunk
	s_and_b64 s[0:1], exec, s[28:29]
	s_mov_b32 s0, 0x2d7a0000
	s_cselect_b32 s0, s0, 0x2efa0000
	s_add_u32 s4, s62, s0
	s_addc_u32 s5, s63, 0
	s_lshl_b32 s0, s47, 7
	s_add_i32 s0, s0, s48
	s_ashr_i32 s1, s0, 31
	s_lshl_b64 s[0:1], s[0:1], 14
	s_add_u32 s0, s4, s0
	s_addc_u32 s1, s5, s1
	v_lshlrev_b32_e32 v0, 4, v106
	v_mov_b32_e32 v1, 0
	v_lshl_add_u64 v[32:33], s[0:1], 0, v[0:1]
	s_movk_i32 s4, 0x1000
	s_mov_b32 s5, 0
	v_lshl_add_u64 v[34:35], v[32:33], 0, s[4:5]
	s_movk_i32 s4, 0x2000
	v_mul_u32_u24_e32 v0, 0x110, v206
	v_lshl_add_u32 v0, v207, 4, v0
	v_add_u32_e32 v0, s39, v0
	v_lshrrev_b32_e32 v1, 4, v106
	v_mul_u32_u24_e32 v1, 0x110, v1
	v_and_b32_e32 v2, 15, v106
	v_lshl_add_u32 v1, v2, 4, v1
	v_add_u32_e32 v1, s39, v1
	ds_write_b128 v0, v[128:131] offset:0
	ds_write_b128 v0, v[132:135] offset:32
	ds_write_b128 v0, v[136:139] offset:64
	ds_write_b128 v0, v[140:143] offset:96
	ds_write_b128 v0, v[160:163] offset:128
	ds_write_b128 v0, v[164:167] offset:160
	ds_write_b128 v0, v[168:171] offset:192
	ds_write_b128 v0, v[172:175] offset:224
	ds_read_b128 v[64:67], v1 offset:0
	ds_read_b128 v[68:71], v1 offset:1088
	ds_read_b128 v[72:75], v1 offset:2176
	ds_read_b128 v[76:79], v1 offset:3264
	ds_read_b128 v[80:83], v1 offset:4352
	ds_read_b128 v[84:87], v1 offset:5440
	ds_read_b128 v[88:91], v1 offset:6528
	ds_read_b128 v[92:95], v1 offset:7616
	s_waitcnt lgkmcnt(7)
	global_store_dwordx4 v[32:33], v[64:67], off
	s_waitcnt lgkmcnt(6)
	global_store_dwordx4 v[32:33], v[68:71], off offset:1024
	s_waitcnt lgkmcnt(5)
	global_store_dwordx4 v[32:33], v[72:75], off offset:2048
	s_waitcnt lgkmcnt(4)
	global_store_dwordx4 v[32:33], v[76:79], off offset:3072
	s_waitcnt lgkmcnt(3)
	global_store_dwordx4 v[34:35], v[80:83], off
	s_waitcnt lgkmcnt(2)
	global_store_dwordx4 v[34:35], v[84:87], off offset:1024
	s_waitcnt lgkmcnt(1)
	global_store_dwordx4 v[34:35], v[88:91], off offset:2048
	s_waitcnt lgkmcnt(0)
	global_store_dwordx4 v[34:35], v[92:95], off offset:3072
	v_lshl_add_u64 v[32:33], v[32:33], 0, s[4:5]
	v_lshl_add_u64 v[34:35], v[34:35], 0, s[4:5]
	ds_write_b128 v0, v[144:147] offset:0
	ds_write_b128 v0, v[148:151] offset:32
	ds_write_b128 v0, v[152:155] offset:64
	ds_write_b128 v0, v[156:159] offset:96
	ds_write_b128 v0, v[176:179] offset:128
	ds_write_b128 v0, v[180:183] offset:160
	ds_write_b128 v0, v[184:187] offset:192
	ds_write_b128 v0, v[188:191] offset:224
	ds_read_b128 v[64:67], v1 offset:0
	ds_read_b128 v[68:71], v1 offset:1088
	ds_read_b128 v[72:75], v1 offset:2176
	ds_read_b128 v[76:79], v1 offset:3264
	ds_read_b128 v[80:83], v1 offset:4352
	ds_read_b128 v[84:87], v1 offset:5440
	ds_read_b128 v[88:91], v1 offset:6528
	ds_read_b128 v[92:95], v1 offset:7616
	s_waitcnt lgkmcnt(7)
	global_store_dwordx4 v[32:33], v[64:67], off
	s_waitcnt lgkmcnt(6)
	global_store_dwordx4 v[32:33], v[68:71], off offset:1024
	s_waitcnt lgkmcnt(5)
	global_store_dwordx4 v[32:33], v[72:75], off offset:2048
	s_waitcnt lgkmcnt(4)
	global_store_dwordx4 v[32:33], v[76:79], off offset:3072
	s_waitcnt lgkmcnt(3)
	global_store_dwordx4 v[34:35], v[80:83], off
	s_waitcnt lgkmcnt(2)
	global_store_dwordx4 v[34:35], v[84:87], off offset:1024
	s_waitcnt lgkmcnt(1)
	global_store_dwordx4 v[34:35], v[88:91], off offset:2048
	s_waitcnt lgkmcnt(0)
	global_store_dwordx4 v[34:35], v[92:95], off offset:3072
	s_branch .LBB0_264
